# GEMM K-loop heads pinned to 64-byte alignment (s_nop fill), otherwise same as v26
# baseline (speedup 1.0000x reference)
.LBB0_344:
	s_ashr_i32 s37, s36, 31
	v_cmp_lt_i64_e32 vcc, s[38:39], v[142:143]
	s_lshl_b64 s[38:39], s[36:37], 20
	s_add_u32 s38, s30, s38
	s_addc_u32 s39, s31, s39
	s_and_b64 s[40:41], vcc, exec
	s_cselect_b32 s37, s39, s45
	s_cselect_b32 s72, s38, s44
	s_ashr_i32 s27, s26, 31
	s_lshl_b64 s[40:41], s[26:27], 20
	s_add_u32 s40, s56, s40
	s_addc_u32 s41, s57, s41
	s_and_b64 s[50:51], vcc, exec
	s_cselect_b32 s27, s41, s47
	s_cselect_b32 s73, s40, s46
	s_add_u32 s44, s44, 0x80080
	s_addc_u32 s45, s45, 0
	s_add_u32 s74, s46, 0x100
	v_mov_b32_e32 v2, 0
	s_addc_u32 s75, s47, 0
	s_mov_b32 s76, -2
	v_mov_b32_e32 v3, v2
	v_mov_b32_e32 v4, v2
	v_mov_b32_e32 v5, v2
	v_mov_b32_e32 v6, v2
	v_mov_b32_e32 v7, v2
	v_mov_b32_e32 v8, v2
	v_mov_b32_e32 v9, v2
	v_mov_b32_e32 v10, v2
	v_mov_b32_e32 v11, v2
	v_mov_b32_e32 v12, v2
	v_mov_b32_e32 v13, v2
	v_mov_b32_e32 v18, v2
	v_mov_b32_e32 v19, v2
	v_mov_b32_e32 v20, v2
	v_mov_b32_e32 v21, v2
	v_mov_b32_e32 v26, v2
	v_mov_b32_e32 v27, v2
	v_mov_b32_e32 v28, v2
	v_mov_b32_e32 v29, v2
	v_mov_b32_e32 v34, v2
	v_mov_b32_e32 v35, v2
	v_mov_b32_e32 v36, v2
	v_mov_b32_e32 v37, v2
	v_mov_b32_e32 v42, v2
	v_mov_b32_e32 v43, v2
	v_mov_b32_e32 v44, v2
	v_mov_b32_e32 v45, v2
	v_mov_b32_e32 v50, v2
	v_mov_b32_e32 v51, v2
	v_mov_b32_e32 v52, v2
	v_mov_b32_e32 v53, v2
	v_mov_b32_e32 v14, v2
	v_mov_b32_e32 v15, v2
	v_mov_b32_e32 v16, v2
	v_mov_b32_e32 v17, v2
	v_mov_b32_e32 v22, v2
	v_mov_b32_e32 v23, v2
	v_mov_b32_e32 v24, v2
	v_mov_b32_e32 v25, v2
	v_mov_b32_e32 v30, v2
	v_mov_b32_e32 v31, v2
	v_mov_b32_e32 v32, v2
	v_mov_b32_e32 v33, v2
	v_mov_b32_e32 v38, v2
	v_mov_b32_e32 v39, v2
	v_mov_b32_e32 v40, v2
	v_mov_b32_e32 v41, v2
	v_mov_b32_e32 v46, v2
	v_mov_b32_e32 v47, v2
	v_mov_b32_e32 v48, v2
	v_mov_b32_e32 v49, v2
	v_mov_b32_e32 v54, v2
	v_mov_b32_e32 v55, v2
	v_mov_b32_e32 v56, v2
	v_mov_b32_e32 v57, v2
	v_mov_b32_e32 v58, v2
	v_mov_b32_e32 v59, v2
	v_mov_b32_e32 v60, v2
	v_mov_b32_e32 v61, v2
	v_mov_b32_e32 v62, v2
	v_mov_b32_e32 v63, v2
	v_mov_b32_e32 v64, v2
	v_mov_b32_e32 v65, v2
	v_mov_b32_e32 v66, v2
	v_mov_b32_e32 v67, v2
	v_mov_b32_e32 v68, v2
	v_mov_b32_e32 v69, v2
	v_mov_b32_e32 v70, v2
	v_mov_b32_e32 v71, v2
	v_mov_b32_e32 v72, v2
	v_mov_b32_e32 v73, v2
	v_mov_b32_e32 v78, v2
	v_mov_b32_e32 v79, v2
	v_mov_b32_e32 v80, v2
	v_mov_b32_e32 v81, v2
	v_mov_b32_e32 v86, v2
	v_mov_b32_e32 v87, v2
	v_mov_b32_e32 v88, v2
	v_mov_b32_e32 v89, v2
	v_mov_b32_e32 v94, v2
	v_mov_b32_e32 v95, v2
	v_mov_b32_e32 v96, v2
	v_mov_b32_e32 v97, v2
	v_mov_b32_e32 v102, v2
	v_mov_b32_e32 v103, v2
	v_mov_b32_e32 v104, v2
	v_mov_b32_e32 v105, v2
	v_mov_b32_e32 v110, v2
	v_mov_b32_e32 v111, v2
	v_mov_b32_e32 v112, v2
	v_mov_b32_e32 v113, v2
	v_mov_b32_e32 v118, v2
	v_mov_b32_e32 v119, v2
	v_mov_b32_e32 v120, v2
	v_mov_b32_e32 v121, v2
	v_mov_b32_e32 v74, v2
	v_mov_b32_e32 v75, v2
	v_mov_b32_e32 v76, v2
	v_mov_b32_e32 v77, v2
	v_mov_b32_e32 v82, v2
	v_mov_b32_e32 v83, v2
	v_mov_b32_e32 v84, v2
	v_mov_b32_e32 v85, v2
	v_mov_b32_e32 v90, v2
	v_mov_b32_e32 v91, v2
	v_mov_b32_e32 v92, v2
	v_mov_b32_e32 v93, v2
	v_mov_b32_e32 v98, v2
	v_mov_b32_e32 v99, v2
	v_mov_b32_e32 v100, v2
	v_mov_b32_e32 v101, v2
	v_mov_b32_e32 v106, v2
	v_mov_b32_e32 v107, v2
	v_mov_b32_e32 v108, v2
	v_mov_b32_e32 v109, v2
	v_mov_b32_e32 v114, v2
	v_mov_b32_e32 v115, v2
	v_mov_b32_e32 v116, v2
	v_mov_b32_e32 v117, v2
	v_mov_b32_e32 v122, v2
	v_mov_b32_e32 v123, v2
	v_mov_b32_e32 v124, v2
	v_mov_b32_e32 v125, v2
	v_mov_b32_e32 v126, v2
	v_mov_b32_e32 v127, v2
	v_mov_b32_e32 v128, v2
	v_mov_b32_e32 v129, v2
	s_cmp_eq_u32 s99, 0
	s_cbranch_scc1 .LBB0_345
	ds_read_b128 v[164:167], v160
	ds_read_b128 v[168:171], v160 offset:1024
	ds_read_b128 v[172:175], v160 offset:2048
	ds_read_b128 v[176:179], v160 offset:3072
	s_add_u32 s46, s44, 0xfff80080
	s_addc_u32 s47, s45, -1
	s_cmp_eq_u32 s76, 28
	s_cselect_b32 s51, s37, s47
	s_cselect_b32 s50, s72, s46
	s_cselect_b32 s47, s27, s75
	s_cselect_b32 s46, s73, s74
	v_lshl_add_u64 v[148:149], s[44:45], 0, v[138:139]
	s_add_i32 m0, s34, 0xc000
	ds_read_b128 v[180:183], v161
	ds_read_b128 v[184:187], v161 offset:1024
	ds_read_b128 v[188:191], v161 offset:2048
	ds_read_b128 v[192:195], v161 offset:3072
	ds_read_b128 v[196:199], v161 offset:4096
	ds_read_b128 v[204:207], v161 offset:5120
	ds_read_b128 v[208:211], v161 offset:6144
	ds_read_b128 v[212:215], v161 offset:7168
	v_lshl_add_u64 v[148:149], s[44:45], 0, v[140:141]
	s_add_i32 m0, s34, 0xe000
	s_nop 0
	s_waitcnt lgkmcnt(8)
	s_barrier
	s_waitcnt lgkmcnt(0)
	s_setprio 1
	s_waitcnt lgkmcnt(0)
	v_mfma_f32_16x16x32_bf16 v[126:129], v[164:167], v[180:183], v[126:129]
	v_mfma_f32_16x16x32_bf16 v[122:125], v[172:175], v[180:183], v[122:125]
	v_mfma_f32_16x16x32_bf16 v[114:117], v[164:167], v[188:191], v[114:117]
	v_mfma_f32_16x16x32_bf16 v[106:109], v[172:175], v[188:191], v[106:109]
	v_mfma_f32_16x16x32_bf16 v[98:101], v[164:167], v[196:199], v[98:101]
	v_mfma_f32_16x16x32_bf16 v[90:93], v[172:175], v[196:199], v[90:93]
	v_mfma_f32_16x16x32_bf16 v[82:85], v[164:167], v[208:211], v[82:85]
	v_mfma_f32_16x16x32_bf16 v[74:77], v[172:175], v[208:211], v[74:77]
	v_mfma_f32_16x16x32_bf16 v[126:129], v[168:171], v[184:187], v[126:129]
	v_mfma_f32_16x16x32_bf16 v[122:125], v[176:179], v[184:187], v[122:125]
	v_mfma_f32_16x16x32_bf16 v[114:117], v[168:171], v[192:195], v[114:117]
	v_mfma_f32_16x16x32_bf16 v[106:109], v[176:179], v[192:195], v[106:109]
	v_mfma_f32_16x16x32_bf16 v[98:101], v[168:171], v[204:207], v[98:101]
	v_mfma_f32_16x16x32_bf16 v[90:93], v[176:179], v[204:207], v[90:93]
	v_mfma_f32_16x16x32_bf16 v[82:85], v[168:171], v[212:215], v[82:85]
	v_mfma_f32_16x16x32_bf16 v[74:77], v[176:179], v[212:215], v[74:77]
	s_setprio 0
	s_barrier
	s_add_i32 s77, s65, s33
	v_lshl_add_u64 v[148:149], s[46:47], 0, v[132:133]
	s_mov_b32 m0, s77
	ds_read_b128 v[216:219], v162
	ds_read_b128 v[220:223], v162 offset:1024
	ds_read_b128 v[224:227], v162 offset:2048
	ds_read_b128 v[228:231], v162 offset:3072
	global_load_lds_dwordx4 v[148:149], off
	v_lshl_add_u64 v[232:233], s[46:47], 0, v[136:137]
	s_add_i32 m0, s77, 0x2000
	s_nop 0
	global_load_lds_dwordx4 v[232:233], off
	s_barrier
	s_waitcnt lgkmcnt(0)
	s_setprio 1
	s_waitcnt lgkmcnt(0)
	v_mfma_f32_16x16x32_bf16 v[118:121], v[216:219], v[180:183], v[118:121]
	v_mfma_f32_16x16x32_bf16 v[110:113], v[224:227], v[180:183], v[110:113]
	v_mfma_f32_16x16x32_bf16 v[102:105], v[216:219], v[188:191], v[102:105]
	v_mfma_f32_16x16x32_bf16 v[94:97], v[224:227], v[188:191], v[94:97]
	v_mfma_f32_16x16x32_bf16 v[86:89], v[216:219], v[196:199], v[86:89]
	v_mfma_f32_16x16x32_bf16 v[78:81], v[224:227], v[196:199], v[78:81]
	v_mfma_f32_16x16x32_bf16 v[70:73], v[216:219], v[208:211], v[70:73]
	v_mfma_f32_16x16x32_bf16 v[66:69], v[224:227], v[208:211], v[66:69]
	v_mfma_f32_16x16x32_bf16 v[118:121], v[220:223], v[184:187], v[118:121]
	v_mfma_f32_16x16x32_bf16 v[110:113], v[228:231], v[184:187], v[110:113]
	v_mfma_f32_16x16x32_bf16 v[102:105], v[220:223], v[192:195], v[102:105]
	v_mfma_f32_16x16x32_bf16 v[94:97], v[228:231], v[192:195], v[94:97]
	v_mfma_f32_16x16x32_bf16 v[86:89], v[220:223], v[204:207], v[86:89]
	v_mfma_f32_16x16x32_bf16 v[78:81], v[228:231], v[204:207], v[78:81]
	v_mfma_f32_16x16x32_bf16 v[70:73], v[220:223], v[212:215], v[70:73]
	v_mfma_f32_16x16x32_bf16 v[66:69], v[228:231], v[212:215], v[66:69]
	s_setprio 0
	s_mov_b32 m0, s34
	v_lshl_add_u64 v[234:235], s[50:51], 0, v[130:131]
	s_barrier
	ds_read_b128 v[180:183], v161 offset:16384
	ds_read_b128 v[184:187], v161 offset:17408
	ds_read_b128 v[188:191], v161 offset:18432
	ds_read_b128 v[192:195], v161 offset:19456
	ds_read_b128 v[196:199], v161 offset:20480
	ds_read_b128 v[204:207], v161 offset:21504
	ds_read_b128 v[208:211], v161 offset:22528
	ds_read_b128 v[212:215], v161 offset:23552
	global_load_lds_dwordx4 v[234:235], off
	v_lshl_add_u64 v[236:237], s[50:51], 0, v[134:135]
	s_mov_b32 m0, s35
	s_nop 0
	global_load_lds_dwordx4 v[236:237], off
	s_barrier
	s_waitcnt lgkmcnt(0)
	s_setprio 1
	s_waitcnt lgkmcnt(0)
	v_mfma_f32_16x16x32_bf16 v[62:65], v[164:167], v[180:183], v[62:65]
	v_mfma_f32_16x16x32_bf16 v[58:61], v[172:175], v[180:183], v[58:61]
	v_mfma_f32_16x16x32_bf16 v[54:57], v[164:167], v[188:191], v[54:57]
	v_mfma_f32_16x16x32_bf16 v[46:49], v[172:175], v[188:191], v[46:49]
	v_mfma_f32_16x16x32_bf16 v[38:41], v[164:167], v[196:199], v[38:41]
	v_mfma_f32_16x16x32_bf16 v[30:33], v[172:175], v[196:199], v[30:33]
	v_mfma_f32_16x16x32_bf16 v[22:25], v[164:167], v[208:211], v[22:25]
	v_mfma_f32_16x16x32_bf16 v[14:17], v[172:175], v[208:211], v[14:17]
	v_mfma_f32_16x16x32_bf16 v[62:65], v[168:171], v[184:187], v[62:65]
	v_mfma_f32_16x16x32_bf16 v[58:61], v[176:179], v[184:187], v[58:61]
	v_mfma_f32_16x16x32_bf16 v[54:57], v[168:171], v[192:195], v[54:57]
	v_mfma_f32_16x16x32_bf16 v[46:49], v[176:179], v[192:195], v[46:49]
	v_mfma_f32_16x16x32_bf16 v[38:41], v[168:171], v[204:207], v[38:41]
	v_mfma_f32_16x16x32_bf16 v[30:33], v[176:179], v[204:207], v[30:33]
	v_mfma_f32_16x16x32_bf16 v[22:25], v[168:171], v[212:215], v[22:25]
	v_mfma_f32_16x16x32_bf16 v[14:17], v[176:179], v[212:215], v[14:17]
	s_setprio 0
	s_barrier
	s_add_u32 s78, s46, 0x80000
	s_addc_u32 s79, s47, 0
	s_add_i32 s77, s66, s33
	v_lshl_add_u64 v[164:165], s[78:79], 0, v[132:133]
	s_mov_b32 m0, s77
	s_nop 0
	global_load_lds_dwordx4 v[164:165], off
	v_lshl_add_u64 v[164:165], s[78:79], 0, v[136:137]
	s_add_i32 m0, s77, 0x2000
	s_nop 0
	global_load_lds_dwordx4 v[164:165], off
	s_waitcnt vmcnt(22)
	s_barrier
	s_setprio 1
	v_mfma_f32_16x16x32_bf16 v[50:53], v[216:219], v[180:183], v[50:53]
	v_mfma_f32_16x16x32_bf16 v[42:45], v[224:227], v[180:183], v[42:45]
	v_mfma_f32_16x16x32_bf16 v[34:37], v[216:219], v[188:191], v[34:37]
	v_mfma_f32_16x16x32_bf16 v[26:29], v[224:227], v[188:191], v[26:29]
	v_mfma_f32_16x16x32_bf16 v[18:21], v[216:219], v[196:199], v[18:21]
	v_mfma_f32_16x16x32_bf16 v[10:13], v[224:227], v[196:199], v[10:13]
	v_mfma_f32_16x16x32_bf16 v[6:9], v[216:219], v[208:211], v[6:9]
	v_mfma_f32_16x16x32_bf16 v[2:5], v[224:227], v[208:211], v[2:5]
	v_mfma_f32_16x16x32_bf16 v[50:53], v[220:223], v[184:187], v[50:53]
	v_mfma_f32_16x16x32_bf16 v[42:45], v[228:231], v[184:187], v[42:45]
	v_mfma_f32_16x16x32_bf16 v[34:37], v[220:223], v[192:195], v[34:37]
	v_mfma_f32_16x16x32_bf16 v[26:29], v[228:231], v[192:195], v[26:29]
	v_mfma_f32_16x16x32_bf16 v[18:21], v[220:223], v[204:207], v[18:21]
	v_mfma_f32_16x16x32_bf16 v[10:13], v[228:231], v[204:207], v[10:13]
	v_mfma_f32_16x16x32_bf16 v[6:9], v[220:223], v[212:215], v[6:9]
	v_mfma_f32_16x16x32_bf16 v[2:5], v[228:231], v[212:215], v[2:5]
	s_setprio 0
	s_add_i32 s77, 0, 0x18000
	v_add_u32_e32 v163, s77, v158
	s_barrier
	s_branch .Ltb_mid_g1
	.p2alignl 6, 3212836864

.LBB0_364:
	s_ashr_i32 s37, s36, 31
	v_cmp_lt_i64_e32 vcc, s[38:39], v[142:143]
	s_lshl_b64 s[38:39], s[36:37], 20
	s_add_u32 s38, s56, s38
	s_addc_u32 s39, s57, s39
	s_and_b64 s[40:41], vcc, exec
	s_cselect_b32 s37, s39, s45
	s_cselect_b32 s72, s38, s44
	s_ashr_i32 s27, s26, 31
	s_lshl_b64 s[40:41], s[26:27], 20
	s_add_u32 s40, s30, s40
	s_addc_u32 s41, s31, s41
	s_and_b64 s[50:51], vcc, exec
	s_cselect_b32 s27, s41, s47
	s_cselect_b32 s73, s40, s46
	s_add_u32 s44, s44, 0x80080
	s_addc_u32 s45, s45, 0
	s_add_u32 s74, s46, 0x100
	v_mov_b32_e32 v2, 0
	s_addc_u32 s75, s47, 0
	s_mov_b32 s76, -2
	v_mov_b32_e32 v3, v2
	v_mov_b32_e32 v4, v2
	v_mov_b32_e32 v5, v2
	v_mov_b32_e32 v6, v2
	v_mov_b32_e32 v7, v2
	v_mov_b32_e32 v8, v2
	v_mov_b32_e32 v9, v2
	v_mov_b32_e32 v10, v2
	v_mov_b32_e32 v11, v2
	v_mov_b32_e32 v12, v2
	v_mov_b32_e32 v13, v2
	v_mov_b32_e32 v18, v2
	v_mov_b32_e32 v19, v2
	v_mov_b32_e32 v20, v2
	v_mov_b32_e32 v21, v2
	v_mov_b32_e32 v26, v2
	v_mov_b32_e32 v27, v2
	v_mov_b32_e32 v28, v2
	v_mov_b32_e32 v29, v2
	v_mov_b32_e32 v34, v2
	v_mov_b32_e32 v35, v2
	v_mov_b32_e32 v36, v2
	v_mov_b32_e32 v37, v2
	v_mov_b32_e32 v42, v2
	v_mov_b32_e32 v43, v2
	v_mov_b32_e32 v44, v2
	v_mov_b32_e32 v45, v2
	v_mov_b32_e32 v50, v2
	v_mov_b32_e32 v51, v2
	v_mov_b32_e32 v52, v2
	v_mov_b32_e32 v53, v2
	v_mov_b32_e32 v14, v2
	v_mov_b32_e32 v15, v2
	v_mov_b32_e32 v16, v2
	v_mov_b32_e32 v17, v2
	v_mov_b32_e32 v22, v2
	v_mov_b32_e32 v23, v2
	v_mov_b32_e32 v24, v2
	v_mov_b32_e32 v25, v2
	v_mov_b32_e32 v30, v2
	v_mov_b32_e32 v31, v2
	v_mov_b32_e32 v32, v2
	v_mov_b32_e32 v33, v2
	v_mov_b32_e32 v38, v2
	v_mov_b32_e32 v39, v2
	v_mov_b32_e32 v40, v2
	v_mov_b32_e32 v41, v2
	v_mov_b32_e32 v46, v2
	v_mov_b32_e32 v47, v2
	v_mov_b32_e32 v48, v2
	v_mov_b32_e32 v49, v2
	v_mov_b32_e32 v54, v2
	v_mov_b32_e32 v55, v2
	v_mov_b32_e32 v56, v2
	v_mov_b32_e32 v57, v2
	v_mov_b32_e32 v58, v2
	v_mov_b32_e32 v59, v2
	v_mov_b32_e32 v60, v2
	v_mov_b32_e32 v61, v2
	v_mov_b32_e32 v62, v2
	v_mov_b32_e32 v63, v2
	v_mov_b32_e32 v64, v2
	v_mov_b32_e32 v65, v2
	v_mov_b32_e32 v66, v2
	v_mov_b32_e32 v67, v2
	v_mov_b32_e32 v68, v2
	v_mov_b32_e32 v69, v2
	v_mov_b32_e32 v70, v2
	v_mov_b32_e32 v71, v2
	v_mov_b32_e32 v72, v2
	v_mov_b32_e32 v73, v2
	v_mov_b32_e32 v78, v2
	v_mov_b32_e32 v79, v2
	v_mov_b32_e32 v80, v2
	v_mov_b32_e32 v81, v2
	v_mov_b32_e32 v86, v2
	v_mov_b32_e32 v87, v2
	v_mov_b32_e32 v88, v2
	v_mov_b32_e32 v89, v2
	v_mov_b32_e32 v94, v2
	v_mov_b32_e32 v95, v2
	v_mov_b32_e32 v96, v2
	v_mov_b32_e32 v97, v2
	v_mov_b32_e32 v102, v2
	v_mov_b32_e32 v103, v2
	v_mov_b32_e32 v104, v2
	v_mov_b32_e32 v105, v2
	v_mov_b32_e32 v110, v2
	v_mov_b32_e32 v111, v2
	v_mov_b32_e32 v112, v2
	v_mov_b32_e32 v113, v2
	v_mov_b32_e32 v118, v2
	v_mov_b32_e32 v119, v2
	v_mov_b32_e32 v120, v2
	v_mov_b32_e32 v121, v2
	v_mov_b32_e32 v74, v2
	v_mov_b32_e32 v75, v2
	v_mov_b32_e32 v76, v2
	v_mov_b32_e32 v77, v2
	v_mov_b32_e32 v82, v2
	v_mov_b32_e32 v83, v2
	v_mov_b32_e32 v84, v2
	v_mov_b32_e32 v85, v2
	v_mov_b32_e32 v90, v2
	v_mov_b32_e32 v91, v2
	v_mov_b32_e32 v92, v2
	v_mov_b32_e32 v93, v2
	v_mov_b32_e32 v98, v2
	v_mov_b32_e32 v99, v2
	v_mov_b32_e32 v100, v2
	v_mov_b32_e32 v101, v2
	v_mov_b32_e32 v106, v2
	v_mov_b32_e32 v107, v2
	v_mov_b32_e32 v108, v2
	v_mov_b32_e32 v109, v2
	v_mov_b32_e32 v114, v2
	v_mov_b32_e32 v115, v2
	v_mov_b32_e32 v116, v2
	v_mov_b32_e32 v117, v2
	v_mov_b32_e32 v122, v2
	v_mov_b32_e32 v123, v2
	v_mov_b32_e32 v124, v2
	v_mov_b32_e32 v125, v2
	v_mov_b32_e32 v126, v2
	v_mov_b32_e32 v127, v2
	v_mov_b32_e32 v128, v2
	v_mov_b32_e32 v129, v2
	.p2alignl 6, 3212836864

.LBB0_908:
	s_ashr_i32 s25, s24, 31
	v_cmp_lt_i64_e32 vcc, s[26:27], v[142:143]
	s_lshl_b64 s[26:27], s[24:25], 20
	s_add_u32 s26, s56, s26
	s_addc_u32 s27, s57, s27
	s_and_b64 s[36:37], vcc, exec
	s_cselect_b32 s25, s27, s41
	s_cselect_b32 s66, s26, s40
	s_ashr_i32 s23, s22, 31
	s_lshl_b64 s[36:37], s[22:23], 20
	s_add_u32 s36, s30, s36
	s_addc_u32 s37, s31, s37
	s_and_b64 s[44:45], vcc, exec
	s_cselect_b32 s23, s37, s43
	s_cselect_b32 s67, s36, s42
	s_add_u32 s40, s40, 0x80080
	s_addc_u32 s41, s41, 0
	s_add_u32 s68, s42, 0x100
	v_mov_b32_e32 v2, 0
	s_addc_u32 s69, s43, 0
	s_mov_b32 s70, -2
	v_mov_b32_e32 v3, v2
	v_mov_b32_e32 v4, v2
	v_mov_b32_e32 v5, v2
	v_mov_b32_e32 v6, v2
	v_mov_b32_e32 v7, v2
	v_mov_b32_e32 v8, v2
	v_mov_b32_e32 v9, v2
	v_mov_b32_e32 v10, v2
	v_mov_b32_e32 v11, v2
	v_mov_b32_e32 v12, v2
	v_mov_b32_e32 v13, v2
	v_mov_b32_e32 v18, v2
	v_mov_b32_e32 v19, v2
	v_mov_b32_e32 v20, v2
	v_mov_b32_e32 v21, v2
	v_mov_b32_e32 v26, v2
	v_mov_b32_e32 v27, v2
	v_mov_b32_e32 v28, v2
	v_mov_b32_e32 v29, v2
	v_mov_b32_e32 v34, v2
	v_mov_b32_e32 v35, v2
	v_mov_b32_e32 v36, v2
	v_mov_b32_e32 v37, v2
	v_mov_b32_e32 v42, v2
	v_mov_b32_e32 v43, v2
	v_mov_b32_e32 v44, v2
	v_mov_b32_e32 v45, v2
	v_mov_b32_e32 v50, v2
	v_mov_b32_e32 v51, v2
	v_mov_b32_e32 v52, v2
	v_mov_b32_e32 v53, v2
	v_mov_b32_e32 v14, v2
	v_mov_b32_e32 v15, v2
	v_mov_b32_e32 v16, v2
	v_mov_b32_e32 v17, v2
	v_mov_b32_e32 v22, v2
	v_mov_b32_e32 v23, v2
	v_mov_b32_e32 v24, v2
	v_mov_b32_e32 v25, v2
	v_mov_b32_e32 v30, v2
	v_mov_b32_e32 v31, v2
	v_mov_b32_e32 v32, v2
	v_mov_b32_e32 v33, v2
	v_mov_b32_e32 v38, v2
	v_mov_b32_e32 v39, v2
	v_mov_b32_e32 v40, v2
	v_mov_b32_e32 v41, v2
	v_mov_b32_e32 v46, v2
	v_mov_b32_e32 v47, v2
	v_mov_b32_e32 v48, v2
	v_mov_b32_e32 v49, v2
	v_mov_b32_e32 v54, v2
	v_mov_b32_e32 v55, v2
	v_mov_b32_e32 v56, v2
	v_mov_b32_e32 v57, v2
	v_mov_b32_e32 v58, v2
	v_mov_b32_e32 v59, v2
	v_mov_b32_e32 v60, v2
	v_mov_b32_e32 v61, v2
	v_mov_b32_e32 v62, v2
	v_mov_b32_e32 v63, v2
	v_mov_b32_e32 v64, v2
	v_mov_b32_e32 v65, v2
	v_mov_b32_e32 v66, v2
	v_mov_b32_e32 v67, v2
	v_mov_b32_e32 v68, v2
	v_mov_b32_e32 v69, v2
	v_mov_b32_e32 v70, v2
	v_mov_b32_e32 v71, v2
	v_mov_b32_e32 v72, v2
	v_mov_b32_e32 v73, v2
	v_mov_b32_e32 v78, v2
	v_mov_b32_e32 v79, v2
	v_mov_b32_e32 v80, v2
	v_mov_b32_e32 v81, v2
	v_mov_b32_e32 v86, v2
	v_mov_b32_e32 v87, v2
	v_mov_b32_e32 v88, v2
	v_mov_b32_e32 v89, v2
	v_mov_b32_e32 v94, v2
	v_mov_b32_e32 v95, v2
	v_mov_b32_e32 v96, v2
	v_mov_b32_e32 v97, v2
	v_mov_b32_e32 v102, v2
	v_mov_b32_e32 v103, v2
	v_mov_b32_e32 v104, v2
	v_mov_b32_e32 v105, v2
	v_mov_b32_e32 v110, v2
	v_mov_b32_e32 v111, v2
	v_mov_b32_e32 v112, v2
	v_mov_b32_e32 v113, v2
	v_mov_b32_e32 v118, v2
	v_mov_b32_e32 v119, v2
	v_mov_b32_e32 v120, v2
	v_mov_b32_e32 v121, v2
	v_mov_b32_e32 v74, v2
	v_mov_b32_e32 v75, v2
	v_mov_b32_e32 v76, v2
	v_mov_b32_e32 v77, v2
	v_mov_b32_e32 v82, v2
	v_mov_b32_e32 v83, v2
	v_mov_b32_e32 v84, v2
	v_mov_b32_e32 v85, v2
	v_mov_b32_e32 v90, v2
	v_mov_b32_e32 v91, v2
	v_mov_b32_e32 v92, v2
	v_mov_b32_e32 v93, v2
	v_mov_b32_e32 v98, v2
	v_mov_b32_e32 v99, v2
	v_mov_b32_e32 v100, v2
	v_mov_b32_e32 v101, v2
	v_mov_b32_e32 v106, v2
	v_mov_b32_e32 v107, v2
	v_mov_b32_e32 v108, v2
	v_mov_b32_e32 v109, v2
	v_mov_b32_e32 v114, v2
	v_mov_b32_e32 v115, v2
	v_mov_b32_e32 v116, v2
	v_mov_b32_e32 v117, v2
	v_mov_b32_e32 v122, v2
	v_mov_b32_e32 v123, v2
	v_mov_b32_e32 v124, v2
	v_mov_b32_e32 v125, v2
	v_mov_b32_e32 v126, v2
	v_mov_b32_e32 v127, v2
	v_mov_b32_e32 v128, v2
	v_mov_b32_e32 v129, v2
	.p2alignl 6, 3212836864
